# nt streaming policy on the once-read ph_rec LDS-DMA fragment loads (on top of T2/B2 stack)
# speedup vs baseline: 1.0167x; 1.0167x over previous
.LBB0_95:
	s_lshl_b32 s3, s2, 5
	s_lshl_b32 s6, s2, 2
	s_add_i32 s7, s3, 64
	v_readlane_b32 s2, v251, 33
	v_readlane_b32 s3, v251, 34
	s_and_b64 s[2:3], s[2:3], exec
	s_cselect_b32 s2, s7, s6
	s_cmp_eq_u32 s0, 0
	s_cselect_b64 s[50:51], -1, 0
	s_and_b64 s[6:7], s[50:51], exec
	v_readlane_b32 s3, v251, 38
	s_cselect_b32 s6, 0, s3
	s_add_i32 s3, s2, s6
	s_and_b64 vcc, exec, s[4:5]
	v_mov_b32_e32 v172, 0
	s_cbranch_vccz .LBB0_97
	s_mul_i32 s7, s3, 12
	s_add_i32 s7, s7, s10
	s_lshl_b32 s7, s7, 1
	s_or_b32 s8, s7, s0
	s_ashr_i32 s9, s8, 31
	s_mul_i32 s7, s8, 0x12000
	v_readlane_b32 s11, v251, 41
	s_mul_hi_i32 s0, s8, 0x12000
	s_add_u32 s38, s11, s7
	v_readlane_b32 s7, v251, 42
	s_addc_u32 s39, s7, s0
	v_lshl_add_u64 v[64:65], s[38:39], 0, v[150:151]
	s_mov_b32 m0, s15
	v_lshl_add_u64 v[66:67], v[64:65], 0, s[42:43]
	s_mov_b64 vcc, 0x400
	v_readlane_b32 s0, v255, 33
	global_load_lds_dwordx4 v[66:67], off nt
	v_lshl_add_u64 v[68:69], v[66:67], 0, vcc
	s_mov_b32 m0, s0
	s_mov_b64 vcc, 0x800
	v_readlane_b32 s0, v255, 34
	global_load_lds_dwordx4 v[68:69], off nt
	v_lshl_add_u64 v[68:69], v[66:67], 0, vcc
	s_mov_b32 m0, s0
	s_mov_b64 vcc, 0xc00
	v_readlane_b32 s48, v255, 17
	global_load_lds_dwordx4 v[68:69], off nt
	v_lshl_add_u64 v[66:67], v[66:67], 0, vcc
	s_add_i32 m0, s15, 0xc00
	v_readlane_b32 s49, v255, 18
	global_load_lds_dwordx4 v[66:67], off nt
	s_nop 0
	v_lshl_add_u64 v[66:67], v[64:65], 0, s[48:49]
	v_readlane_b32 s48, v255, 19
	s_add_i32 m0, s15, 0x1000
	v_readlane_b32 s49, v255, 20
	global_load_lds_dwordx4 v[66:67], off nt
	s_nop 0
	v_lshl_add_u64 v[66:67], v[64:65], 0, s[48:49]
	v_readlane_b32 s48, v255, 21
	s_add_i32 m0, s15, 0x1400
	v_readlane_b32 s49, v255, 22
	global_load_lds_dwordx4 v[66:67], off nt
	s_nop 0
	v_lshl_add_u64 v[66:67], v[64:65], 0, s[48:49]
	v_readlane_b32 s48, v255, 23
	s_add_i32 m0, s15, 0x1800
	v_readlane_b32 s49, v255, 24
	global_load_lds_dwordx4 v[66:67], off nt
	s_nop 0
	v_lshl_add_u64 v[66:67], v[64:65], 0, s[48:49]
	v_readlane_b32 s48, v255, 25
	s_add_i32 m0, s15, 0x1c00
	v_readlane_b32 s49, v255, 26
	global_load_lds_dwordx4 v[66:67], off nt
	s_nop 0
	v_lshl_add_u64 v[66:67], v[64:65], 0, s[48:49]
	v_readlane_b32 s48, v255, 27
	s_add_i32 m0, s15, 0x2000
	v_readlane_b32 s49, v255, 28
	global_load_lds_dwordx4 v[66:67], off nt
	s_nop 0
	v_lshl_add_u64 v[66:67], v[64:65], 0, s[48:49]
	v_readlane_b32 s48, v255, 29
	s_add_i32 m0, s15, 0x2400
	v_readlane_b32 s49, v255, 30
	global_load_lds_dwordx4 v[66:67], off nt
	s_nop 0
	v_lshl_add_u64 v[66:67], v[64:65], 0, s[48:49]
	v_readlane_b32 s48, v255, 31
	s_add_i32 m0, s15, 0x2800
	v_readlane_b32 s49, v255, 32
	global_load_lds_dwordx4 v[66:67], off nt
	s_nop 0
	v_lshl_add_u64 v[66:67], v[64:65], 0, s[48:49]
	s_add_i32 m0, s15, 0x2c00
	v_mov_b32_e32 v163, v129
	global_load_lds_dwordx4 v[66:67], off nt
	v_lshl_add_u64 v[66:67], v[64:65], 0, s[16:17]
	s_add_i32 m0, s15, 0x3000
	v_lshl_add_u64 v[64:65], v[64:65], 0, s[26:27]
	global_load_lds_dwordx4 v[66:67], off nt
	s_add_i32 m0, s15, 0x3400
	s_mov_b32 s0, 0xe000
	global_load_lds_dwordx4 v[64:65], off nt
	v_lshl_add_u64 v[64:65], s[38:39], 0, v[162:163]
	v_lshl_add_u64 v[64:65], v[64:65], 0, s[46:47]
	v_add_co_u32_e32 v68, vcc, s0, v64
	s_mov_b64 s[38:39], 0xe000
	s_nop 0
	v_addc_co_u32_e32 v69, vcc, 0, v65, vcc
	s_lshl_b64 s[8:9], s[8:9], 2
	v_readlane_b32 s0, v251, 29
	v_lshl_add_u64 v[66:67], v[64:65], 0, s[38:39]
	v_add_co_u32_e32 v64, vcc, 0x10000, v64
	s_add_u32 s8, s0, s8
	v_readlane_b32 s0, v251, 30
	v_addc_co_u32_e32 v65, vcc, 0, v65, vcc
	s_addc_u32 s9, s0, s9
	global_load_dwordx4 v[76:79], v[68:69], off
	global_load_dwordx4 v[72:75], v[66:67], off offset:1024
	s_nop 0
	global_load_dwordx4 v[68:71], v[64:65], off
	s_nop 0
	global_load_dwordx4 v[64:67], v[64:65], off offset:1024
	s_nop 0
	global_load_dword v172, v129, s[8:9]

.Lrec_helper:
	s_cmp_ge_u32 s10, s95
	s_cbranch_scc1 .LBB0_101
	s_bitcmp1_b32 s10, 0
	s_cselect_b32 s3, 0xe000, 0
	v_lshl_add_u64 v[80:81], s[80:81], 0, v[168:169]
	s_mov_b64 s[8:9], 0x1d511000
	s_add_i32 s3, s15, s3
	v_lshl_add_u64 v[82:83], v[80:81], 0, s[8:9]
	s_mov_b32 m0, s3
	s_mov_b64 s[8:9], 0x1d511400
	global_load_lds_dwordx4 v[82:83], off nt
	v_lshl_add_u64 v[82:83], v[80:81], 0, s[8:9]
	s_add_i32 m0, s3, 0x400
	s_mov_b64 s[8:9], 0x1d511800
	global_load_lds_dwordx4 v[82:83], off nt
	v_lshl_add_u64 v[82:83], v[80:81], 0, s[8:9]
	s_add_i32 m0, s3, 0x800
	s_mov_b64 s[8:9], 0x1d511c00
	global_load_lds_dwordx4 v[82:83], off nt
	v_lshl_add_u64 v[82:83], v[80:81], 0, s[8:9]
	s_add_i32 m0, s3, 0xc00
	s_mov_b64 s[8:9], 0x1d512000
	global_load_lds_dwordx4 v[82:83], off nt
	v_lshl_add_u64 v[82:83], v[80:81], 0, s[8:9]
	s_add_i32 m0, s3, 0x1000
	s_mov_b64 s[8:9], 0x1d512400
	global_load_lds_dwordx4 v[82:83], off nt
	v_lshl_add_u64 v[82:83], v[80:81], 0, s[8:9]
	s_add_i32 m0, s3, 0x1400
	s_mov_b64 s[8:9], 0x1d512800
	global_load_lds_dwordx4 v[82:83], off nt
	v_lshl_add_u64 v[82:83], v[80:81], 0, s[8:9]
	s_add_i32 m0, s3, 0x1800
	s_mov_b64 s[8:9], 0x1d512c00
	global_load_lds_dwordx4 v[82:83], off nt
	v_lshl_add_u64 v[82:83], v[80:81], 0, s[8:9]
	s_add_i32 m0, s3, 0x1c00
	s_mov_b64 s[8:9], 0x1d513000
	global_load_lds_dwordx4 v[82:83], off nt
	v_lshl_add_u64 v[82:83], v[80:81], 0, s[8:9]
	s_add_i32 m0, s3, 0x2000
	s_mov_b64 s[8:9], 0x1d513400
	global_load_lds_dwordx4 v[82:83], off nt
	v_lshl_add_u64 v[82:83], v[80:81], 0, s[8:9]
	s_add_i32 m0, s3, 0x2400
	s_mov_b64 s[8:9], 0x1d513800
	global_load_lds_dwordx4 v[82:83], off nt
	v_lshl_add_u64 v[82:83], v[80:81], 0, s[8:9]
	s_add_i32 m0, s3, 0x2800
	s_mov_b64 s[8:9], 0x1d513c00
	global_load_lds_dwordx4 v[82:83], off nt
	v_lshl_add_u64 v[82:83], v[80:81], 0, s[8:9]
	s_add_i32 m0, s3, 0x2c00
	s_mov_b64 s[8:9], 0x1d514000
	global_load_lds_dwordx4 v[82:83], off nt
	v_lshl_add_u64 v[82:83], v[80:81], 0, s[8:9]
	s_add_i32 m0, s3, 0x3000
	s_mov_b64 s[8:9], 0x1d514400
	global_load_lds_dwordx4 v[82:83], off nt
	v_lshl_add_u64 v[80:81], v[80:81], 0, s[8:9]
	s_add_i32 m0, s3, 0x3400
	global_load_lds_dwordx4 v[80:81], off nt
	s_waitcnt vmcnt(0)
	s_branch .LBB0_101
